# speedup vs baseline: 1.0061x; 1.0061x over previous
; template <int DQK, int MODE> ...
;     ...
;   auto lstore = [&](const TRegs& R, int st) {
;     u16* Ks = lds + st * STG;
;     u16* Vs = Ks + KT;
; #pragma unroll
;     for (int i = 0; i < NKL; ++i) {
;       int c = tid + i * 256;
;       int row = c / KCH, cc = c % KCH;
;       *(u32x4*)(Ks + row * KST + cc * 8) = R.k[i];
;     }
; #pragma unroll
;     for (int i = 0; i < 2; ++i) {
;       int c = tid + i * 256;
;       int d = c >> 3, cc = c & 7;
;       u32x2 lo = {R.v[i].x, R.v[i].y}, hi = {R.v[i].z, R.v[i].w};
;       *(u32x2*)(Vs + d * VST + cc * 8) = lo;
;       *(u32x2*)(Vs + d * VST + cc * 8 + 4) = hi;
;     }
;     ...
;   f32x16 O[2];
; #pragma unroll
;   for (int du = 0; du < 2; ++du)
; #pragma unroll
;     for (int r = 0; r < 16; ++r) O[du][r] = 0.f;
;   float m_run = 0.f, lsum = 0.f;
;   bool first = true;
;   float carry = active ? 1.f : 0.f;
;   const int dir = (MODE == 2) ? -1 : 1;
;   const int jstart = (MODE == 2) ? jhi : jlo;
;   const int ntile = jhi - jlo + 1;
;     ...
;   {
;     TRegs R0, R1;
;     gload(R0, jstart);
;     if (ntile > 1) gload(R1, jstart + dir);
.LBB0_985:
	v_lshlrev_b32_e32 v176, 3, v15
	v_mov_b32_e32 v49, 0
	s_cmp_lt_i32 s4, 0xfff00000
	v_mov_b32_e32 v48, 0
	v_mov_b32_e32 v47, 0
	v_mov_b32_e32 v46, 0
	v_mov_b32_e32 v45, 0
	v_mov_b32_e32 v44, 0
	v_mov_b32_e32 v43, 0
	v_mov_b32_e32 v42, 0
	v_mov_b32_e32 v41, 0
	v_mov_b32_e32 v40, 0
	v_mov_b32_e32 v39, 0
	v_mov_b32_e32 v38, 0
	v_mov_b32_e32 v37, 0
	v_mov_b32_e32 v36, 0
	v_mov_b32_e32 v35, 0
	v_mov_b32_e32 v34, 0
	v_mov_b32_e32 v33, 0
	v_mov_b32_e32 v32, 0
	v_mov_b32_e32 v31, 0
	v_mov_b32_e32 v30, 0
	v_mov_b32_e32 v29, 0
	v_mov_b32_e32 v28, 0
	v_mov_b32_e32 v27, 0
	v_mov_b32_e32 v26, 0
	v_mov_b32_e32 v25, 0
	v_mov_b32_e32 v24, 0
	v_mov_b32_e32 v23, 0
	v_mov_b32_e32 v22, 0
	v_mov_b32_e32 v21, 0
	v_mov_b32_e32 v20, 0
	v_mov_b32_e32 v19, 0
	v_mov_b32_e32 v18, 0
	v_mov_b32_e32 v177, 0
	s_cbranch_scc1 .LBB0_1002
	v_lshl_add_u64 v[178:179], v[4:5], 1, s[16:17]
	v_ashrrev_i32_e32 v5, 7, v14
	v_cndmask_b32_e64 v5, 0, v5, s[0:1]
	v_add_u32_e32 v199, s3, v5
	v_max_i32_e32 v5, 0x100000, v199
	s_movk_i32 s0, 0xd0
	v_add_u32_e32 v200, 0xfff00000, v5
	v_mul_lo_u32 v5, v171, s0
	v_lshl_add_u32 v201, v4, 1, v5
	v_mul_lo_u32 v4, v173, s0
	v_lshl_add_u32 v202, v6, 1, v4
	v_mul_lo_u32 v4, v175, s0
	v_lshl_add_u32 v203, v10, 1, v4
	v_lshrrev_b32_e32 v4, 3, v14
	s_movk_i32 s4, 0x98
	v_mad_u64_u32 v[184:185], s[0:1], v4, s4, v[2:3]
	v_lshrrev_b32_e32 v4, 3, v16
	v_mad_u64_u32 v[186:187], s[0:1], v4, s4, v[2:3]
	v_lshlrev_b32_e32 v2, 1, v176
	v_mul_u32_u24_e32 v4, 0x68, v172
	v_lshl_add_u32 v185, v4, 1, v2
	v_sub_u32_e32 v2, v2, v176
	v_mul_u32_u24_e32 v4, 0x4c, v172
	s_mov_b32 s13, s37
	v_lshl_add_u32 v187, v4, 1, v2
	s_lshl_b64 s[0:1], s[12:13], 13
	v_and_b32_e32 v2, 7, v14
	v_lshl_or_b32 v4, v2, 4, s0
	v_mov_b32_e32 v5, s1
	v_lshl_add_u64 v[180:181], v[6:7], 1, s[16:17]
	v_lshl_add_u64 v[6:7], v[8:9], 1, v[4:5]
	v_lshl_add_u64 v[4:5], v[12:13], 1, v[4:5]
	v_mov_b32_e32 v16, v3
	v_mov_b32_e32 v17, v3
	v_lshl_add_u64 v[182:183], v[10:11], 1, s[16:17]
	v_lshl_add_u64 v[188:189], s[14:15], 0, v[6:7]
	v_lshl_add_u64 v[190:191], s[14:15], 0, v[4:5]
	v_mov_b32_e32 v2, v3
	v_mov_b32_e32 v4, v3
	v_mov_b32_e32 v5, v3
	v_mov_b32_e32 v6, v3
	v_mov_b32_e32 v7, v3
	v_mov_b32_e32 v8, v3
	v_mov_b32_e32 v9, v3
	v_mov_b32_e32 v10, v3
	v_mov_b32_e32 v11, v3
	v_mov_b32_e32 v12, v3
	v_mov_b32_e32 v13, v3
	v_mov_b32_e32 v14, v3
	v_mov_b32_e32 v15, v3
	v_mov_b64_e32 v[32:33], v[16:17]
	v_mov_b64_e32 v[48:49], v[16:17]
	s_mov_b32 s3, 3
	s_lshl_b32 s4, s12, 6
	s_mov_b64 s[0:1], -1
	v_mov_b32_e32 v177, 0
	s_xor_b64 s[14:15], vcc, -1
	v_mov_b64_e32 v[30:31], v[14:15]
	v_mov_b64_e32 v[28:29], v[12:13]
	v_mov_b64_e32 v[26:27], v[10:11]
	v_mov_b64_e32 v[24:25], v[8:9]
	v_mov_b64_e32 v[22:23], v[6:7]
	v_mov_b64_e32 v[20:21], v[4:5]
	v_mov_b64_e32 v[18:19], v[2:3]
	v_mov_b64_e32 v[46:47], v[14:15]
	v_mov_b64_e32 v[44:45], v[12:13]
	v_mov_b64_e32 v[42:43], v[10:11]
	v_mov_b64_e32 v[40:41], v[8:9]
	v_mov_b64_e32 v[38:39], v[6:7]
	v_mov_b64_e32 v[36:37], v[4:5]
	v_mov_b64_e32 v[34:35], v[2:3]
	v_mov_b32_e32 v2, 0
	v_mov_b64_e32 v[228:229], 0
	v_mov_b64_e32 v[230:231], 0
	v_mov_b64_e32 v[232:233], 0
	v_mov_b64_e32 v[234:235], 0
	v_mov_b64_e32 v[236:237], 0
	v_mov_b64_e32 v[238:239], 0
	v_mov_b64_e32 v[240:241], 0
	v_mov_b64_e32 v[242:243], 0
	s_waitcnt vmcnt(0)
	v_add_u32_e32 v226, 0x3400, v184
	ds_write_b128 v201, v[106:109]
	ds_write_b128 v202, v[110:113]
	ds_write_b128 v203, v[114:117]
	ds_write2_b64 v226, v[118:119], v[120:121] offset1:1
	v_add_u32_e32 v226, 0x3400, v186
	ds_write2_b64 v226, v[130:131], v[132:133] offset1:1
	v_add_u32_e32 v220, s4, v171
	v_add_u32_e32 v220, 0xfc000040, v220
	v_add_u32_e32 v222, s4, v173
	v_mad_i64_i32 v[220:221], vcc, v220, s85, v[178:179]
	v_add_u32_e32 v222, 0xfc000040, v222
	v_mad_i64_i32 v[222:223], vcc, v222, s85, v[180:181]
	v_add_u32_e32 v224, s4, v175
	v_add_u32_e32 v224, 0xfc000040, v224
	v_mad_i64_i32 v[224:225], vcc, v224, s85, v[182:183]
	v_lshl_add_u64 v[244:245], v[188:189], 0, s[10:11]
	v_add_co_u32_e32 v244, vcc, 0x2000, v244
	s_nop 1
	v_addc_co_u32_e32 v245, vcc, -2, v245, vcc
	v_lshl_add_u64 v[248:249], v[190:191], 0, s[10:11]
	v_add_co_u32_e32 v248, vcc, 0x2000, v248
	s_nop 1
	v_addc_co_u32_e32 v249, vcc, -2, v249, vcc
	s_nop 0
	v_readfirstlane_b32 s72, v220
	v_readfirstlane_b32 s73, v221
	v_readfirstlane_b32 s74, v244
	v_readfirstlane_b32 s75, v245
	s_lshl_b32 s76, s85, 6
	s_nop 1
	v_subrev_u32_e32 v220, s72, v220
	v_subrev_u32_e32 v222, s72, v222
	v_subrev_u32_e32 v224, s72, v224
	v_subrev_u32_e32 v244, s74, v244
	v_subrev_u32_e32 v248, s74, v248
	s_branch .LBB0_990
	.p2align	6

; template <int DQK, int MODE> ...
;     ...
;   auto lstore = [&](const TRegs& R, int st) {
;     u16* Ks = lds + st * STG;
;     u16* Vs = Ks + KT;
; #pragma unroll
;     for (int i = 0; i < NKL; ++i) {
;       int c = tid + i * 256;
;       int row = c / KCH, cc = c % KCH;
;       *(u32x4*)(Ks + row * KST + cc * 8) = R.k[i];
;     }
; #pragma unroll
;     for (int i = 0; i < 2; ++i) {
;       int c = tid + i * 256;
;       int d = c >> 3, cc = c & 7;
;       u32x2 lo = {R.v[i].x, R.v[i].y}, hi = {R.v[i].z, R.v[i].w};
;       *(u32x2*)(Vs + d * VST + cc * 8) = lo;
;       *(u32x2*)(Vs + d * VST + cc * 8 + 4) = hi;
;     }
;     ...
;   f32x16 O[2];
; #pragma unroll
;   for (int du = 0; du < 2; ++du)
; #pragma unroll
;     for (int r = 0; r < 16; ++r) O[du][r] = 0.f;
;   float m_run = 0.f, lsum = 0.f;
;   bool first = true;
;   float carry = active ? 1.f : 0.f;
;   const int dir = (MODE == 2) ? -1 : 1;
;   const int jstart = (MODE == 2) ? jhi : jlo;
;   const int ntile = jhi - jlo + 1;
;     ...
;   {
;     TRegs R0, R1;
;     gload(R0, jstart);
;     if (ntile > 1) gload(R1, jstart + dir);
.LBB0_2122:
	v_lshlrev_b32_e32 v174, 3, v13
	v_mov_b32_e32 v47, 0
	s_cmp_lt_i32 s9, 0xfff00000
	v_mov_b32_e32 v46, 0
	v_mov_b32_e32 v45, 0
	v_mov_b32_e32 v44, 0
	v_mov_b32_e32 v43, 0
	v_mov_b32_e32 v42, 0
	v_mov_b32_e32 v41, 0
	v_mov_b32_e32 v40, 0
	v_mov_b32_e32 v39, 0
	v_mov_b32_e32 v38, 0
	v_mov_b32_e32 v37, 0
	v_mov_b32_e32 v36, 0
	v_mov_b32_e32 v35, 0
	v_mov_b32_e32 v34, 0
	v_mov_b32_e32 v33, 0
	v_mov_b32_e32 v32, 0
	v_mov_b32_e32 v31, 0
	v_mov_b32_e32 v30, 0
	v_mov_b32_e32 v29, 0
	v_mov_b32_e32 v28, 0
	v_mov_b32_e32 v27, 0
	v_mov_b32_e32 v26, 0
	v_mov_b32_e32 v25, 0
	v_mov_b32_e32 v24, 0
	v_mov_b32_e32 v23, 0
	v_mov_b32_e32 v22, 0
	v_mov_b32_e32 v21, 0
	v_mov_b32_e32 v20, 0
	v_mov_b32_e32 v19, 0
	v_mov_b32_e32 v18, 0
	v_mov_b32_e32 v17, 0
	v_mov_b32_e32 v16, 0
	v_mov_b32_e32 v175, 0
	s_cbranch_scc1 .LBB0_2139
	v_lshl_add_u64 v[176:177], v[2:3], 1, s[12:13]
	v_ashrrev_i32_e32 v3, 7, v12
	v_cndmask_b32_e64 v3, 0, v3, s[46:47]
	v_add_u32_e32 v197, s14, v3
	v_max_i32_e32 v3, 0x100000, v197
	s_movk_i32 s9, 0xd0
	v_add_u32_e32 v199, 0xfff00000, v3
	v_mul_lo_u32 v3, v169, s9
	v_lshl_add_u32 v200, v2, 1, v3
	v_mul_lo_u32 v2, v171, s9
	v_lshl_add_u32 v201, v4, 1, v2
	v_mul_lo_u32 v2, v173, s9
	v_lshl_add_u32 v202, v8, 1, v2
	v_lshrrev_b32_e32 v2, 3, v12
	v_lshl_add_u64 v[178:179], v[4:5], 1, s[12:13]
	v_lshl_add_u64 v[180:181], v[8:9], 1, s[12:13]
	v_mad_u64_u32 v[182:183], s[12:13], v2, s95, v[0:1]
	v_lshrrev_b32_e32 v2, 3, v14
	v_mad_u64_u32 v[184:185], s[12:13], v2, s95, v[0:1]
	v_lshlrev_b32_e32 v0, 1, v174
	v_mul_u32_u24_e32 v2, 0x68, v170
	v_lshl_add_u32 v183, v2, 1, v0
	v_sub_u32_e32 v0, v0, v174
	v_mul_u32_u24_e32 v2, 0x4c, v170
	s_mov_b32 s9, s19
	v_lshl_add_u32 v185, v2, 1, v0
	s_lshl_b64 s[12:13], s[8:9], 13
	v_and_b32_e32 v0, 7, v12
	v_lshl_or_b32 v2, v0, 4, s12
	v_mov_b32_e32 v3, s13
	v_lshl_add_u64 v[4:5], v[6:7], 1, v[2:3]
	v_lshl_add_u64 v[2:3], v[10:11], 1, v[2:3]
	v_mov_b32_e32 v14, v1
	v_mov_b32_e32 v15, v1
	v_lshl_add_u64 v[186:187], s[10:11], 0, v[4:5]
	v_lshl_add_u64 v[188:189], s[10:11], 0, v[2:3]
	v_mov_b32_e32 v0, v1
	v_mov_b32_e32 v2, v1
	v_mov_b32_e32 v3, v1
	v_mov_b32_e32 v4, v1
	v_mov_b32_e32 v5, v1
	v_mov_b32_e32 v6, v1
	v_mov_b32_e32 v7, v1
	v_mov_b32_e32 v8, v1
	v_mov_b32_e32 v9, v1
	v_mov_b32_e32 v10, v1
	v_mov_b32_e32 v11, v1
	v_mov_b32_e32 v12, v1
	v_mov_b32_e32 v13, v1
	v_mov_b64_e32 v[30:31], v[14:15]
	v_mov_b64_e32 v[46:47], v[14:15]
	s_mov_b32 s17, 3
	s_lshl_b32 s9, s8, 6
	s_mov_b64 s[10:11], -1
	v_mov_b32_e32 v175, 0
	s_xor_b64 s[12:13], vcc, -1
	v_mov_b64_e32 v[28:29], v[12:13]
	v_mov_b64_e32 v[26:27], v[10:11]
	v_mov_b64_e32 v[24:25], v[8:9]
	v_mov_b64_e32 v[22:23], v[6:7]
	v_mov_b64_e32 v[20:21], v[4:5]
	v_mov_b64_e32 v[18:19], v[2:3]
	v_mov_b64_e32 v[16:17], v[0:1]
	v_mov_b64_e32 v[44:45], v[12:13]
	v_mov_b64_e32 v[42:43], v[10:11]
	v_mov_b64_e32 v[40:41], v[8:9]
	v_mov_b64_e32 v[38:39], v[6:7]
	v_mov_b64_e32 v[36:37], v[4:5]
	v_mov_b64_e32 v[34:35], v[2:3]
	v_mov_b64_e32 v[32:33], v[0:1]
	v_mov_b32_e32 v0, 0
	v_mov_b64_e32 v[228:229], 0
	v_mov_b64_e32 v[230:231], 0
	v_mov_b64_e32 v[232:233], 0
	v_mov_b64_e32 v[234:235], 0
	v_mov_b64_e32 v[236:237], 0
	v_mov_b64_e32 v[238:239], 0
	v_mov_b64_e32 v[240:241], 0
	v_mov_b64_e32 v[242:243], 0
	s_waitcnt vmcnt(0)
	v_add_u32_e32 v226, 0x3400, v182
	ds_write_b128 v200, v[104:107]
	ds_write_b128 v201, v[108:111]
	ds_write_b128 v202, v[112:115]
	ds_write2_b64 v226, v[116:117], v[118:119] offset1:1
	v_add_u32_e32 v226, 0x3400, v184
	ds_write2_b64 v226, v[128:129], v[130:131] offset1:1
	v_add_u32_e32 v220, s9, v169
	v_add_u32_e32 v220, 0xfc000040, v220
	v_add_u32_e32 v222, s9, v171
	v_mad_i64_i32 v[220:221], vcc, v220, s87, v[176:177]
	v_add_u32_e32 v222, 0xfc000040, v222
	v_mad_i64_i32 v[222:223], vcc, v222, s87, v[178:179]
	v_add_u32_e32 v224, s9, v173
	v_add_u32_e32 v224, 0xfc000040, v224
	v_mad_i64_i32 v[224:225], vcc, v224, s87, v[180:181]
	v_lshl_add_u64 v[244:245], v[186:187], 0, s[2:3]
	v_add_co_u32_e32 v244, vcc, 0x2000, v244
	s_nop 1
	v_addc_co_u32_e32 v245, vcc, -2, v245, vcc
	v_lshl_add_u64 v[248:249], v[188:189], 0, s[2:3]
	v_add_co_u32_e32 v248, vcc, 0x2000, v248
	s_nop 1
	v_addc_co_u32_e32 v249, vcc, -2, v249, vcc
	s_nop 0
	v_readfirstlane_b32 s72, v220
	v_readfirstlane_b32 s73, v221
	v_readfirstlane_b32 s74, v244
	v_readfirstlane_b32 s75, v245
	s_lshl_b32 s76, s87, 6
	s_nop 1
	v_subrev_u32_e32 v220, s72, v220
	v_subrev_u32_e32 v222, s72, v222
	v_subrev_u32_e32 v224, s72, v224
	v_subrev_u32_e32 v244, s74, v244
	v_subrev_u32_e32 v248, s74, v248
	s_branch .LBB0_2127
	.p2align	6
